# v30 + diff-attention causal mask block rewritten: one distance per lane, compare against inline constants, three compare results in flight, no nops (127 -> 68 instrs per diagonal tile)
# speedup vs baseline: 1.0039x; 1.0032x over previous
.Lskip_v2_0:
.LBB0_625:
	s_sub_i32 s73, s18, 63
	s_cmp_gt_i32 s73, s27
	s_cbranch_scc1 .LBB0_638
	s_bitcmp1_b32 s72, 0
	s_cselect_b32 s72, 0x2400, 0
	v_add_u32_e32 v32, s72, v188
	s_setprio 1
	ds_read_b128 v[214:217], v32
	ds_read_b128 v[218:221], v32 offset:4608
	ds_read_b128 v[222:225], v32 offset:32
	ds_read_b128 v[226:229], v32 offset:4640
	ds_read_b128 v[230:233], v32 offset:64
	ds_read_b128 v[234:237], v32 offset:4672
	ds_read_b128 v[238:241], v32 offset:96
	ds_read_b128 v[244:247], v32 offset:4704
	s_waitcnt lgkmcnt(7)
	v_mfma_f32_32x32x16_bf16 v[114:129], v[214:217], v[146:149], v[98:113]
	s_waitcnt lgkmcnt(6)
	v_mfma_f32_32x32x16_bf16 v[130:145], v[218:221], v[146:149], v[98:113]
	s_waitcnt lgkmcnt(5)
	v_mfma_f32_32x32x16_bf16 v[114:129], v[222:225], v[150:153], v[114:129]
	s_waitcnt lgkmcnt(4)
	v_mfma_f32_32x32x16_bf16 v[130:145], v[226:229], v[150:153], v[130:145]
	s_waitcnt lgkmcnt(3)
	v_mfma_f32_32x32x16_bf16 v[114:129], v[230:233], v[154:157], v[114:129]
	s_waitcnt lgkmcnt(2)
	v_mfma_f32_32x32x16_bf16 v[130:145], v[234:237], v[154:157], v[130:145]
	s_waitcnt lgkmcnt(1)
	v_mfma_f32_32x32x16_bf16 v[114:129], v[238:241], v[158:161], v[114:129]
	s_waitcnt lgkmcnt(0)
	v_mfma_f32_32x32x16_bf16 v[130:145], v[244:247], v[158:161], v[130:145]
	s_setprio 0
	s_cmp_le_i32 s18, s76
	s_cbranch_scc1 .LBB0_628
	v_add_u32_e32 v32, s18, v190
	v_sub_u32_e32 v32, v32, v166
	s_nop 1
	v_cmp_ge_i32_e32 vcc, 63, v32
	v_cmp_gt_i32_e64 s[72:73], 63, v32
	v_cmp_ge_i32_e64 s[74:75], 61, v32
	v_cndmask_b32_e32 v114, v208, v114, vcc
	v_cndmask_b32_e64 v115, v208, v115, s[72:73]
	v_cndmask_b32_e64 v116, v208, v116, s[74:75]
	v_cmp_ge_i32_e32 vcc, 60, v32
	v_cmp_ge_i32_e64 s[72:73], 55, v32
	v_cmp_ge_i32_e64 s[74:75], 54, v32
	v_cndmask_b32_e32 v117, v208, v117, vcc
	v_cndmask_b32_e64 v118, v208, v118, s[72:73]
	v_cndmask_b32_e64 v119, v208, v119, s[74:75]
	v_cmp_ge_i32_e32 vcc, 53, v32
	v_cmp_ge_i32_e64 s[72:73], 52, v32
	v_cmp_ge_i32_e64 s[74:75], 47, v32
	v_cndmask_b32_e32 v120, v208, v120, vcc
	v_cndmask_b32_e64 v121, v208, v121, s[72:73]
	v_cndmask_b32_e64 v122, v208, v122, s[74:75]
	v_cmp_ge_i32_e32 vcc, 46, v32
	v_cmp_ge_i32_e64 s[72:73], 45, v32
	v_cmp_ge_i32_e64 s[74:75], 44, v32
	v_cndmask_b32_e32 v123, v208, v123, vcc
	v_cndmask_b32_e64 v124, v208, v124, s[72:73]
	v_cndmask_b32_e64 v125, v208, v125, s[74:75]
	v_cmp_ge_i32_e32 vcc, 39, v32
	v_cmp_ge_i32_e64 s[72:73], 38, v32
	v_cmp_ge_i32_e64 s[74:75], 37, v32
	v_cndmask_b32_e32 v126, v208, v126, vcc
	v_cndmask_b32_e64 v127, v208, v127, s[72:73]
	v_cndmask_b32_e64 v128, v208, v128, s[74:75]
	v_cmp_ge_i32_e32 vcc, 36, v32
	v_cmp_ge_i32_e64 s[72:73], 31, v32
	v_cmp_ge_i32_e64 s[74:75], 30, v32
	v_cndmask_b32_e32 v129, v208, v129, vcc
	v_cndmask_b32_e64 v130, v208, v130, s[72:73]
	v_cndmask_b32_e64 v131, v208, v131, s[74:75]
	v_cmp_ge_i32_e32 vcc, 29, v32
	v_cmp_ge_i32_e64 s[72:73], 28, v32
	v_cmp_ge_i32_e64 s[74:75], 23, v32
	v_cndmask_b32_e32 v132, v208, v132, vcc
	v_cndmask_b32_e64 v133, v208, v133, s[72:73]
	v_cndmask_b32_e64 v134, v208, v134, s[74:75]
	v_cmp_ge_i32_e32 vcc, 22, v32
	v_cmp_ge_i32_e64 s[72:73], 21, v32
	v_cmp_ge_i32_e64 s[74:75], 20, v32
	v_cndmask_b32_e32 v135, v208, v135, vcc
	v_cndmask_b32_e64 v136, v208, v136, s[72:73]
	v_cndmask_b32_e64 v137, v208, v137, s[74:75]
	v_cmp_ge_i32_e32 vcc, 15, v32
	v_cmp_ge_i32_e64 s[72:73], 14, v32
	v_cmp_ge_i32_e64 s[74:75], 13, v32
	v_cndmask_b32_e32 v138, v208, v138, vcc
	v_cndmask_b32_e64 v139, v208, v139, s[72:73]
	v_cndmask_b32_e64 v140, v208, v140, s[74:75]
	v_cmp_ge_i32_e32 vcc, 12, v32
	v_cmp_ge_i32_e64 s[72:73], 7, v32
	v_cmp_ge_i32_e64 s[74:75], 6, v32
	v_cndmask_b32_e32 v141, v208, v141, vcc
	v_cndmask_b32_e64 v142, v208, v142, s[72:73]
	v_cndmask_b32_e64 v143, v208, v143, s[74:75]
	v_cmp_ge_i32_e32 vcc, 5, v32
	v_cmp_ge_i32_e64 s[72:73], 4, v32
	s_nop 0
	v_cndmask_b32_e32 v144, v208, v144, vcc
	v_cndmask_b32_e64 v145, v208, v145, s[72:73]

.Lskip_v2_1:
.LBB0_825:
	s_sub_i32 s73, s18, 63
	s_cmp_gt_i32 s73, s26
	s_cbranch_scc1 .LBB0_838
	s_bitcmp1_b32 s72, 0
	s_cselect_b32 s72, 0x2400, 0
	v_add_u32_e32 v32, s72, v188
	s_setprio 1
	ds_read_b128 v[214:217], v32
	ds_read_b128 v[218:221], v32 offset:4608
	ds_read_b128 v[222:225], v32 offset:32
	ds_read_b128 v[226:229], v32 offset:4640
	ds_read_b128 v[230:233], v32 offset:64
	ds_read_b128 v[234:237], v32 offset:4672
	ds_read_b128 v[238:241], v32 offset:96
	ds_read_b128 v[244:247], v32 offset:4704
	s_waitcnt lgkmcnt(7)
	v_mfma_f32_32x32x16_bf16 v[114:129], v[214:217], v[146:149], v[98:113]
	s_waitcnt lgkmcnt(6)
	v_mfma_f32_32x32x16_bf16 v[130:145], v[218:221], v[146:149], v[98:113]
	s_waitcnt lgkmcnt(5)
	v_mfma_f32_32x32x16_bf16 v[114:129], v[222:225], v[150:153], v[114:129]
	s_waitcnt lgkmcnt(4)
	v_mfma_f32_32x32x16_bf16 v[130:145], v[226:229], v[150:153], v[130:145]
	s_waitcnt lgkmcnt(3)
	v_mfma_f32_32x32x16_bf16 v[114:129], v[230:233], v[154:157], v[114:129]
	s_waitcnt lgkmcnt(2)
	v_mfma_f32_32x32x16_bf16 v[130:145], v[234:237], v[154:157], v[130:145]
	s_waitcnt lgkmcnt(1)
	v_mfma_f32_32x32x16_bf16 v[114:129], v[238:241], v[158:161], v[114:129]
	s_waitcnt lgkmcnt(0)
	v_mfma_f32_32x32x16_bf16 v[130:145], v[244:247], v[158:161], v[130:145]
	s_setprio 0
	s_cmp_le_i32 s18, s76
	s_cbranch_scc1 .LBB0_828
	v_add_u32_e32 v32, s18, v190
	v_sub_u32_e32 v32, v32, v166
	s_nop 1
	v_cmp_ge_i32_e32 vcc, 63, v32
	v_cmp_gt_i32_e64 s[72:73], 63, v32
	v_cmp_ge_i32_e64 s[74:75], 61, v32
	v_cndmask_b32_e32 v114, v208, v114, vcc
	v_cndmask_b32_e64 v115, v208, v115, s[72:73]
	v_cndmask_b32_e64 v116, v208, v116, s[74:75]
	v_cmp_ge_i32_e32 vcc, 60, v32
	v_cmp_ge_i32_e64 s[72:73], 55, v32
	v_cmp_ge_i32_e64 s[74:75], 54, v32
	v_cndmask_b32_e32 v117, v208, v117, vcc
	v_cndmask_b32_e64 v118, v208, v118, s[72:73]
	v_cndmask_b32_e64 v119, v208, v119, s[74:75]
	v_cmp_ge_i32_e32 vcc, 53, v32
	v_cmp_ge_i32_e64 s[72:73], 52, v32
	v_cmp_ge_i32_e64 s[74:75], 47, v32
	v_cndmask_b32_e32 v120, v208, v120, vcc
	v_cndmask_b32_e64 v121, v208, v121, s[72:73]
	v_cndmask_b32_e64 v122, v208, v122, s[74:75]
	v_cmp_ge_i32_e32 vcc, 46, v32
	v_cmp_ge_i32_e64 s[72:73], 45, v32
	v_cmp_ge_i32_e64 s[74:75], 44, v32
	v_cndmask_b32_e32 v123, v208, v123, vcc
	v_cndmask_b32_e64 v124, v208, v124, s[72:73]
	v_cndmask_b32_e64 v125, v208, v125, s[74:75]
	v_cmp_ge_i32_e32 vcc, 39, v32
	v_cmp_ge_i32_e64 s[72:73], 38, v32
	v_cmp_ge_i32_e64 s[74:75], 37, v32
	v_cndmask_b32_e32 v126, v208, v126, vcc
	v_cndmask_b32_e64 v127, v208, v127, s[72:73]
	v_cndmask_b32_e64 v128, v208, v128, s[74:75]
	v_cmp_ge_i32_e32 vcc, 36, v32
	v_cmp_ge_i32_e64 s[72:73], 31, v32
	v_cmp_ge_i32_e64 s[74:75], 30, v32
	v_cndmask_b32_e32 v129, v208, v129, vcc
	v_cndmask_b32_e64 v130, v208, v130, s[72:73]
	v_cndmask_b32_e64 v131, v208, v131, s[74:75]
	v_cmp_ge_i32_e32 vcc, 29, v32
	v_cmp_ge_i32_e64 s[72:73], 28, v32
	v_cmp_ge_i32_e64 s[74:75], 23, v32
	v_cndmask_b32_e32 v132, v208, v132, vcc
	v_cndmask_b32_e64 v133, v208, v133, s[72:73]
	v_cndmask_b32_e64 v134, v208, v134, s[74:75]
	v_cmp_ge_i32_e32 vcc, 22, v32
	v_cmp_ge_i32_e64 s[72:73], 21, v32
	v_cmp_ge_i32_e64 s[74:75], 20, v32
	v_cndmask_b32_e32 v135, v208, v135, vcc
	v_cndmask_b32_e64 v136, v208, v136, s[72:73]
	v_cndmask_b32_e64 v137, v208, v137, s[74:75]
	v_cmp_ge_i32_e32 vcc, 15, v32
	v_cmp_ge_i32_e64 s[72:73], 14, v32
	v_cmp_ge_i32_e64 s[74:75], 13, v32
	v_cndmask_b32_e32 v138, v208, v138, vcc
	v_cndmask_b32_e64 v139, v208, v139, s[72:73]
	v_cndmask_b32_e64 v140, v208, v140, s[74:75]
	v_cmp_ge_i32_e32 vcc, 12, v32
	v_cmp_ge_i32_e64 s[72:73], 7, v32
	v_cmp_ge_i32_e64 s[74:75], 6, v32
	v_cndmask_b32_e32 v141, v208, v141, vcc
	v_cndmask_b32_e64 v142, v208, v142, s[72:73]
	v_cndmask_b32_e64 v143, v208, v143, s[74:75]
	v_cmp_ge_i32_e32 vcc, 5, v32
	v_cmp_ge_i32_e64 s[72:73], 4, v32
	s_nop 0
	v_cndmask_b32_e32 v144, v208, v144, vcc
	v_cndmask_b32_e64 v145, v208, v145, s[72:73]
